# layer-0 input projection: rs_precompute split version too (row-sum loads before the first LDS-DMA pieces), on top of the early-barrier GEMM loops
# speedup vs baseline: 1.0057x; 1.0057x over previous
.LBB0_137:
	s_add_u32 s98, s64, 0x83600
	s_addc_u32 s99, s65, 0
	v_mov_b32_e32 v8, 0
	global_load_dwordx4 v[0:3], v8, s[98:99] sc1
	global_load_dwordx4 v[4:7], v8, s[98:99] offset:16 sc1
	s_waitcnt vmcnt(0)
	v_bcnt_u32_b32 v8, v0, v8
	v_bcnt_u32_b32 v8, v1, v8
	v_bcnt_u32_b32 v8, v2, v8
	v_bcnt_u32_b32 v8, v3, v8
	v_bcnt_u32_b32 v8, v4, v8
	v_bcnt_u32_b32 v8, v5, v8
	v_bcnt_u32_b32 v8, v6, v8
	v_bcnt_u32_b32 v8, v7, v8
	s_nop 1
	v_readfirstlane_b32 s98, v8
	s_nop 3
	s_cmp_eq_u32 s98, 8
	s_cselect_b32 s101, 1, 0
	s_cmp_eq_u32 s66, 0x100
	s_cselect_b32 s101, s101, 0
	v_mov_b32_e32 v0, v181
	s_add_u32 s68, s64, 0x200000
	v_and_b32_e32 v2, 0xff, v0
	v_ashrrev_i32_e32 v4, 8, v0
	v_lshlrev_b32_e32 v0, 2, v2
	v_lshl_or_b32 v0, v4, 10, v0
	s_addc_u32 s69, s65, 0
	s_ashr_i32 s3, s2, 31
	v_add_u32_e32 v0, 0, v0
	v_add_u32_e32 v3, 0x20000, v0
	v_mov_b64_e32 v[0:1], s[2:3]
	s_ashr_i32 s73, s66, 31
	s_mov_b32 s72, s66
	v_mad_i64_i32 v[0:1], s[0:1], s66, v4, v[0:1]
	s_lshl_b64 s[0:1], s[72:73], 1
	s_nop 0
	v_writelane_b32 v247, s0, 28
	s_mov_b64 s[4:5], 0x380
	s_mov_b32 s10, 0x92492493
	v_writelane_b32 v247, s1, 29
	s_mov_b64 s[0:1], 0
	s_cmp_eq_u32 s66, 0x100
	s_cbranch_scc0 .Lrs_orig_i0
	v_and_b32_e32 v230, 0xff, v181
	s_and_b32 s6, s2, 7
	s_lshr_b32 s7, s2, 3
	s_lshl_b32 s6, s6, 4
	s_and_b32 s8, s7, 7
	s_add_i32 s6, s6, s8
	v_lshlrev_b32_e32 v230, 6, v230
	s_lshl_b32 s9, s6, 14
	s_add_u32 s20, s68, s9
	s_addc_u32 s21, s69, 0
	s_add_u32 s98, s20, 0x20000
	s_addc_u32 s99, s21, 0
	global_load_dwordx4 v[196:199], v230, s[20:21] offset:0
	global_load_dwordx4 v[200:203], v230, s[20:21] offset:16
	global_load_dwordx4 v[204:207], v230, s[20:21] offset:32
	global_load_dwordx4 v[208:211], v230, s[20:21] offset:48
	global_load_dwordx4 v[212:215], v230, s[98:99] offset:0
	global_load_dwordx4 v[216:219], v230, s[98:99] offset:16
	global_load_dwordx4 v[220:223], v230, s[98:99] offset:32
	global_load_dwordx4 v[224:227], v230, s[98:99] offset:48
	s_branch .LBB0_141
.Lrs_orig_i0:
	v_mov_b32_e32 v4, 0x358637bd
	v_mov_b32_e32 v5, 0x70
	v_mov_b32_e32 v6, 0x71
	s_branch .LBB0_139

.LBB0_143:
	s_add_u32 s74, s64, 0x12200000
	s_addc_u32 s75, s65, 0
	s_add_u32 s42, s64, 0x6200000
	s_addc_u32 s43, s65, 0
	s_add_u32 s44, s64, 0x40000
	s_addc_u32 s45, s65, 0
	s_add_u32 s76, s64, 0x3200000
	s_addc_u32 s77, s65, 0
	s_add_u32 s20, s64, 0x400000
	s_addc_u32 s21, s65, 0
	s_andn2_b64 vcc, exec, s[0:1]
	s_cbranch_vccnz .LBB0_327
	v_ashrrev_i32_e32 v1, 31, v8
	v_lshrrev_b32_e32 v1, 26, v1
	v_add_u32_e32 v1, v8, v1
	v_ashrrev_i32_e32 v9, 6, v1
	v_bfe_i32 v1, v8, 27, 1
	v_lshlrev_b32_e32 v0, 4, v8
	v_lshrrev_b32_e32 v1, 22, v1
	v_add_u32_e32 v1, v0, v1
	v_and_b32_e32 v1, 0xfffffc00, v1
	v_sub_u32_e32 v1, v0, v1
	v_lshrrev_b32_e32 v2, 4, v1
	v_bitop3_b32 v1, v2, v1, 32 bitop3:0x6c
	v_ashrrev_i32_e32 v3, 31, v1
	v_lshrrev_b32_e32 v3, 26, v3
	v_add_u32_e32 v3, v1, v3
	v_lshlrev_b32_e32 v2, 3, v9
	v_ashrrev_i32_e32 v10, 6, v3
	v_and_b32_e32 v3, 0xc0, v3
	v_and_b32_e32 v2, -16, v2
	v_sub_u32_e32 v1, v1, v3
	v_mov_b32_e32 v3, 1
	v_add_u32_e32 v2, v10, v2
	v_ashrrev_i16_sdwa v1, v3, sext(v1) dst_sel:DWORD dst_unused:UNUSED_PAD src0_sel:DWORD src1_sel:BYTE_0
	v_lshlrev_b32_e32 v4, 5, v9
	v_bfe_i32 v11, v1, 0, 16
	v_lshlrev_b32_e32 v1, 1, v2
	v_lshrrev_b32_e32 v5, 2, v2
	v_and_b32_e32 v6, 3, v10
	s_mov_b32 s1, 0x1fffe0
	v_and_b32_e32 v4, 32, v4
	v_and_b32_e32 v1, 24, v1
	v_and_b32_e32 v5, 4, v5
	v_and_or_b32 v6, v2, s1, v6
	v_or3_b32 v1, v6, v5, v1
	v_add_lshl_u32 v4, v4, v11, 1
	v_add_u32_e32 v0, 0x2000, v0
	v_lshl_add_u32 v146, v1, 11, v4
	v_ashrrev_i32_e32 v1, 31, v0
	v_lshrrev_b32_e32 v1, 22, v1
	v_add_u32_e32 v1, v0, v1
	v_ashrrev_i32_e32 v12, 10, v1
	v_mul_i32_i24_e32 v1, 0x400, v12
	v_sub_u32_e32 v0, v0, v1
	v_lshrrev_b32_e32 v1, 4, v0
	v_bitop3_b32 v0, v1, v0, 32 bitop3:0x6c
	v_lshl_add_u32 v144, v2, 11, v4
	v_ashrrev_i32_e32 v2, 31, v0
	v_lshrrev_b32_e32 v2, 26, v2
	v_add_u32_e32 v2, v0, v2
	v_lshlrev_b32_e32 v1, 3, v12
	v_ashrrev_i32_e32 v13, 6, v2
	v_and_b32_e32 v2, 0xc0, v2
	v_and_b32_e32 v1, -16, v1
	v_sub_u32_e32 v0, v0, v2
	s_ashr_i32 s0, s4, 6
	v_add_u32_e32 v1, v13, v1
	v_ashrrev_i16_sdwa v0, v3, sext(v0) dst_sel:DWORD dst_unused:UNUSED_PAD src0_sel:DWORD src1_sel:BYTE_0
	v_and_b32_e32 v3, 3, v13
	s_ashr_i32 s11, s10, 31
	s_ashr_i32 s9, s8, 31
	v_and_or_b32 v3, v1, s1, v3
	s_ashr_i32 s1, s4, 8
	s_lshl_b32 s33, s0, 10
	s_lshl_b64 s[6:7], s[10:11], 19
	s_lshl_b64 s[22:23], s[8:9], 19
	s_add_u32 s78, s20, s22
	v_lshlrev_b32_e32 v4, 5, v12
	v_bfe_i32 v14, v0, 0, 16
	v_lshlrev_b32_e32 v0, 1, v1
	v_lshrrev_b32_e32 v2, 2, v1
	s_addc_u32 s79, s21, s23
	s_add_i32 s82, s33, 0
	v_and_b32_e32 v4, 32, v4
	v_and_b32_e32 v0, 24, v0
	v_and_b32_e32 v2, 4, v2
	s_add_i32 m0, s82, 0x10000
	v_or3_b32 v0, v3, v2, v0
	v_add_lshl_u32 v2, v4, v14, 1
	global_load_lds_dwordx4 v146, s[78:79]
	s_add_i32 m0, s82, 0x12000
	v_lshl_add_u32 v150, v0, 11, v2
	s_add_u32 s22, s78, 0x40000
	global_load_lds_dwordx4 v150, s[78:79]
	s_addc_u32 s23, s79, 0
	s_add_i32 m0, s82, 0x14000
	v_lshl_add_u32 v148, v1, 11, v2
	global_load_lds_dwordx4 v146, s[22:23]
	s_add_i32 m0, s82, 0x16000
	s_add_u32 s70, s74, s6
	s_addc_u32 s71, s75, s7
	s_add_i32 s83, s82, 0x2000
	global_load_lds_dwordx4 v150, s[22:23]
	s_mov_b32 m0, s82
	s_add_u32 s6, s70, 0x40000
	global_load_lds_dwordx4 v144, s[70:71]
	s_mov_b32 m0, s83
	s_addc_u32 s7, s71, 0
	s_add_i32 s84, s82, 0x4000
	global_load_lds_dwordx4 v148, s[70:71]
	s_mov_b32 m0, s84
	s_add_i32 s85, s82, 0x6000
	global_load_lds_dwordx4 v144, s[6:7]
	s_mov_b32 m0, s85
	v_mov_b32_e32 v153, 0
	global_load_lds_dwordx4 v148, s[6:7]
	s_cmp_eq_u32 s66, 0x100
	s_cbranch_scc0 .Lrs_skipb_i0
	v_lshrrev_b32_e32 v231, 8, v181
	v_and_b32_e32 v228, 0xff, v181
	v_mov_b32_e32 v229, 0x358637bd
	v_readfirstlane_b32 s98, v231
	v_lshlrev_b32_e32 v228, 2, v228
	v_lshl_add_u32 v228, v231, 10, v228
	v_add_u32_e32 v228, 0x20000, v228
	s_lshr_b32 s99, s2, 3
	s_lshl4_add_u32 s99, s98, s99
	s_lshl4_add_u32 s99, s98, s99
	s_waitcnt vmcnt(8)
	v_add_f32_e32 v232, v196, v197
	v_add_f32_e32 v230, v198, v199
	v_add_f32_e32 v232, v232, v230
	v_add_f32_e32 v233, v200, v201
	v_add_f32_e32 v230, v202, v203
	v_add_f32_e32 v233, v233, v230
	v_add_f32_e32 v234, v204, v205
	v_add_f32_e32 v230, v206, v207
	v_add_f32_e32 v234, v234, v230
	v_add_f32_e32 v235, v208, v209
	v_add_f32_e32 v230, v210, v211
	v_add_f32_e32 v235, v235, v230
	v_add_f32_e32 v232, v232, v233
	v_add_f32_e32 v232, v232, v234
	v_add_f32_e32 v232, v232, v235
	v_fmamk_f32 v232, v232, 0x3a800000, v229
	v_rsq_f32_e32 v236, v232
	v_add_f32_e32 v232, v212, v213
	v_add_f32_e32 v230, v214, v215
	v_add_f32_e32 v232, v232, v230
	v_add_f32_e32 v233, v216, v217
	v_add_f32_e32 v230, v218, v219
	v_add_f32_e32 v233, v233, v230
	v_add_f32_e32 v234, v220, v221
	v_add_f32_e32 v230, v222, v223
	v_add_f32_e32 v234, v234, v230
	v_add_f32_e32 v235, v224, v225
	v_add_f32_e32 v230, v226, v227
	v_add_f32_e32 v235, v235, v230
	v_add_f32_e32 v232, v232, v233
	v_add_f32_e32 v232, v232, v234
	v_add_f32_e32 v232, v232, v235
	v_fmamk_f32 v232, v232, 0x3a800000, v229
	v_rsq_f32_e32 v237, v232
	s_cmp_ge_i32 s99, 56
	s_cselect_b64 vcc, -1, 0
	v_cndmask_b32_e32 v230, v236, v237, vcc
	ds_write_b32 v228, v230 offset:0
	s_cmp_ge_i32 s99, -8
	s_cselect_b64 vcc, -1, 0
	v_cndmask_b32_e32 v230, v236, v237, vcc
	ds_write_b32 v228, v230 offset:2048
.Lrs_skipb_i0:
	s_waitcnt lgkmcnt(0)
	v_mov_b32_e32 v147, v153
	v_mov_b32_e32 v151, v153
	v_mov_b32_e32 v145, v153
	v_mov_b32_e32 v149, v153
	s_cmp_eq_u32 s1, 1
	s_mov_b32 s23, 0
	v_lshl_add_u64 v[6:7], s[78:79], 0, v[146:147]
	v_lshl_add_u64 v[4:5], s[78:79], 0, v[150:151]
	v_lshl_add_u64 v[0:1], s[70:71], 0, v[144:145]
	s_cselect_b64 s[24:25], -1, 0
	s_cmp_lg_u32 s1, 1
	v_lshl_add_u64 v[2:3], s[70:71], 0, v[148:149]
	s_cbranch_scc1 .LBB0_146
	s_barrier
